# phase-10 SwiGLU epilogue: per-row rstd of the next tile loaded at the head of this tile's epilogue and reduced behind its last store (kept in registers the K loop never touches); first tile at phase e
# speedup vs baseline: 1.0141x; 1.0007x over previous
.LBB0_1089:
	s_lshl_b32 s5, s6, 5
	s_mov_b64 s[6:7], 0x80
	s_and_b32 s10, s5, 0x60
	s_add_i32 m0, s47, 0x18000
	v_lshl_add_u64 v[6:7], v[6:7], 0, s[6:7]
	s_ashr_i32 s52, s90, 31
	s_lshl_b32 s8, s3, 13
	s_lshl_b32 s28, s10, 7
	s_waitcnt vmcnt(4)
	s_barrier
	global_load_lds_dwordx4 v[6:7], off
	v_lshl_add_u64 v[4:5], v[4:5], 0, s[6:7]
	s_add_i32 m0, s47, 0x1a000
	s_add_i32 s53, s47, 0x8000
	s_add_i32 s54, s47, 0xa000
	global_load_lds_dwordx4 v[4:5], off
	v_lshl_add_u64 v[2:3], v[2:3], 0, s[6:7]
	s_mov_b32 m0, s53
	s_add_u32 s12, s42, 0x40080
	global_load_lds_dwordx4 v[2:3], off
	v_lshl_add_u64 v[0:1], v[0:1], 0, s[6:7]
	s_mov_b32 m0, s54
	s_addc_u32 s13, s43, 0
	global_load_lds_dwordx4 v[0:1], off
	s_add_i32 m0, s47, 0x1c000
	v_lshl_add_u64 v[0:1], s[12:13], 0, v[132:133]
	global_load_lds_dwordx4 v[0:1], off
	v_lshl_add_u64 v[0:1], s[12:13], 0, v[128:129]
	s_add_i32 m0, s47, 0x1e000
	v_bfe_u32 v2, v9, 4, 2
	global_load_lds_dwordx4 v[0:1], off
	v_and_b32_e32 v1, 15, v9
	v_lshlrev_b32_e32 v0, 4, v2
	v_lshlrev_b32_e32 v3, 2, v9
	v_lshl_or_b32 v155, s3, 6, v1
	v_lshl_or_b32 v1, v1, 6, v0
	v_and_b32_e32 v3, 32, v3
	v_bitop3_b32 v4, v1, s8, v3 bitop3:0xde
	v_bitop3_b32 v159, v1, s28, v3 bitop3:0xde
	v_mov_b32_e32 v1, v133
	v_lshl_add_u64 v[136:137], s[0:1], 0, v[0:1]
	v_lshlrev_b32_e32 v0, 14, v13
	v_and_b32_e32 v0, 0xffff8000, v0
	v_lshl_add_u32 v0, v12, 11, v0
	v_and_b32_e32 v1, 1, v13
	v_lshl_or_b32 v0, v1, 6, v0
	v_lshl_add_u32 v138, v14, 1, v0
	v_lshlrev_b32_e32 v0, 14, v8
	v_and_b32_e32 v0, 0xffff8000, v0
	v_lshl_add_u32 v0, v10, 11, v0
	v_and_b32_e32 v1, 1, v8
	s_waitcnt vmcnt(6)
	v_lshl_or_b32 v0, v1, 6, v0
	v_lshl_add_u32 v140, v11, 1, v0
	s_add_i32 s56, 0, 0x10000
	s_add_i32 s57, 0, 0x14000
	v_mbcnt_lo_u32_b32 v0, -1, 0
	s_sext_i32_i8 s5, s2
	s_mov_b32 s55, s90
	v_lshl_or_b32 v163, v2, 3, s10
	v_mov_b32_e32 v139, v133
	v_mov_b32_e32 v141, v133
	v_mov_b64_e32 v[142:143], 0xb00
	v_mov_b64_e32 v[144:145], 0xaff
	v_add_u32_e32 v167, s56, v159
	v_add_u32_e32 v171, 0, v4
	v_add_u32_e32 v175, s57, v159
	v_mbcnt_hi_u32_b32 v177, -1, v0
	s_mov_b32 s8, 0x3a800000
	s_mov_b32 s10, 0x358637bd
	s_mov_b32 s58, 0x800000
	s_movk_i32 s59, 0x1600
	s_mov_b32 s96, s4
	s_mov_b32 s97, s5
	v_lshl_add_u32 v168, s4, 8, v155
	v_ashrrev_i32_e32 v169, 31, v168
	v_or_b32_e32 v164, 16, v168
	v_lshlrev_b64 v[146:147], 6, v[168:169]
	v_ashrrev_i32_e32 v165, 31, v164
	v_or_b32_e32 v160, 32, v168
	v_lshl_add_u64 v[146:147], v[136:137], 0, v[146:147]
	v_lshlrev_b64 v[148:149], 6, v[164:165]
	v_ashrrev_i32_e32 v161, 31, v160
	v_lshl_add_u64 v[148:149], v[136:137], 0, v[148:149]
	global_load_dwordx4 v[178:181], v[146:147], off
	global_load_dwordx4 v[182:185], v[148:149], off
	v_lshlrev_b64 v[146:147], 6, v[160:161]
	v_or_b32_e32 v156, 48, v168
	v_lshl_add_u64 v[146:147], v[136:137], 0, v[146:147]
	v_ashrrev_i32_e32 v157, 31, v156
	global_load_dwordx4 v[186:189], v[146:147], off
	v_lshlrev_b64 v[146:147], 6, v[156:157]
	v_lshl_add_u64 v[146:147], v[136:137], 0, v[146:147]
	global_load_dwordx4 v[196:199], v[146:147], off
	v_add_u32_e32 v152, 0x80, v168
	v_ashrrev_i32_e32 v153, 31, v152
	v_lshlrev_b64 v[146:147], 6, v[152:153]
	v_add_u32_e32 v150, 0x90, v168
	v_lshl_add_u64 v[146:147], v[136:137], 0, v[146:147]
	v_ashrrev_i32_e32 v151, 31, v150
	global_load_dwordx4 v[200:203], v[146:147], off
	v_lshlrev_b64 v[146:147], 6, v[150:151]
	v_lshl_add_u64 v[146:147], v[136:137], 0, v[146:147]
	global_load_dwordx4 v[204:207], v[146:147], off
	v_and_b32_e32 v147, 64, v177
	v_add_u32_e32 v148, 0xa0, v168
	v_add_u32_e32 v146, 0xb0, v168
	v_add_u32_e32 v154, 64, v147
	v_ashrrev_i32_e32 v149, 31, v148
	v_ashrrev_i32_e32 v147, 31, v146
	v_lshlrev_b64 v[208:209], 6, v[148:149]
	v_lshlrev_b64 v[210:211], 6, v[146:147]
	v_lshl_add_u64 v[208:209], v[136:137], 0, v[208:209]
	v_lshl_add_u64 v[212:213], v[136:137], 0, v[210:211]
	global_load_dwordx4 v[208:211], v[208:209], off
	s_nop 0
	global_load_dwordx4 v[212:215], v[212:213], off
	v_xor_b32_e32 v151, 16, v177
	v_cmp_lt_i32_e32 vcc, v151, v154
	v_xor_b32_e32 v153, 32, v177
	v_mov_b64_e32 v[190:191], s[10:11]
	v_cndmask_b32_e32 v151, v177, v151, vcc
	v_lshlrev_b32_e32 v147, 2, v151
	v_cmp_lt_i32_e32 vcc, v153, v154
	v_lshl_or_b32 v172, s5, 7, v163
	s_waitcnt vmcnt(0)
	v_mov_b32_e32 v216, v179
	v_mov_b32_e32 v217, v180
	v_mov_b32_e32 v179, v181
	v_mov_b32_e32 v180, v183
	v_mov_b32_e32 v181, v184
	v_mov_b32_e32 v183, v185
	v_pk_add_f32 v[178:179], v[216:217], v[178:179]
	v_pk_add_f32 v[180:181], v[180:181], v[182:183]
	v_mov_b32_e32 v183, v178
	v_mov_b32_e32 v182, v180
	v_mov_b32_e32 v178, v181
	v_mov_b32_e32 v184, v187
	v_mov_b32_e32 v185, v188
	v_mov_b32_e32 v187, v189
	v_mov_b32_e32 v188, v197
	v_mov_b32_e32 v189, v198
	v_mov_b32_e32 v197, v199
	v_pk_add_f32 v[178:179], v[182:183], v[178:179]
	v_pk_add_f32 v[184:185], v[184:185], v[186:187]
	v_pk_add_f32 v[186:187], v[188:189], v[196:197]
	ds_bpermute_b32 v183, v147, v179
	ds_bpermute_b32 v182, v147, v178
	v_mov_b32_e32 v180, v186
	v_mov_b32_e32 v181, v184
	v_mov_b32_e32 v184, v187
	v_pk_add_f32 v[180:181], v[180:181], v[184:185]
	ds_bpermute_b32 v185, v147, v181
	ds_bpermute_b32 v184, v147, v180
	v_cndmask_b32_e32 v153, v177, v153, vcc
	v_lshlrev_b32_e32 v149, 2, v153
	s_waitcnt lgkmcnt(0)
	v_pk_add_f32 v[178:179], v[178:179], v[182:183]
	ds_bpermute_b32 v183, v149, v179
	ds_bpermute_b32 v182, v149, v178
	v_pk_add_f32 v[180:181], v[180:181], v[184:185]
	ds_bpermute_b32 v185, v149, v181
	ds_bpermute_b32 v184, v149, v180
	v_mov_b32_e32 v186, v201
	s_waitcnt lgkmcnt(2)
	v_pk_add_f32 v[178:179], v[178:179], v[182:183]
	v_mov_b32_e32 v187, v202
	v_mov_b32_e32 v201, v203
	v_mov_b32_e32 v188, v205
	v_pk_fma_f32 v[178:179], v[178:179], s[8:9], v[190:191] op_sel_hi:[1,0,0]
	v_mov_b32_e32 v189, v206
	v_mov_b32_e32 v205, v207
	v_pk_add_f32 v[186:187], v[186:187], v[200:201]
	v_mul_f32_e32 v151, 0x4b800000, v179
	v_cmp_gt_f32_e32 vcc, s58, v179
	v_pk_add_f32 v[182:183], v[188:189], v[204:205]
	s_waitcnt lgkmcnt(0)
	v_pk_add_f32 v[180:181], v[180:181], v[184:185]
	v_cndmask_b32_e32 v151, v179, v151, vcc
	v_mov_b32_e32 v184, v182
	v_mov_b32_e32 v185, v186
	v_mov_b32_e32 v186, v183
	v_rsq_f32_e32 v151, v151
	v_pk_add_f32 v[182:183], v[184:185], v[186:187]
	ds_bpermute_b32 v185, v147, v183
	ds_bpermute_b32 v184, v147, v182
	v_pk_fma_f32 v[180:181], v[180:181], s[8:9], v[190:191] op_sel_hi:[1,0,0]
	v_mul_f32_e32 v153, 0x4b800000, v178
	v_cmp_gt_f32_e64 s[0:1], s58, v178
	v_mul_f32_e32 v157, 0x45800000, v151
	v_mul_f32_e32 v154, 0x4b800000, v181
	v_cndmask_b32_e64 v153, v178, v153, s[0:1]
	v_cmp_gt_f32_e64 s[4:5], s58, v181
	v_cndmask_b32_e32 v178, v151, v157, vcc
	v_mul_f32_e32 v151, 0x4b800000, v180
	v_cmp_gt_f32_e32 vcc, s58, v180
	v_cndmask_b32_e64 v154, v181, v154, s[4:5]
	v_rsq_f32_e32 v153, v153
	v_cndmask_b32_e32 v151, v180, v151, vcc
	s_waitcnt lgkmcnt(0)
	v_pk_add_f32 v[180:181], v[182:183], v[184:185]
	ds_bpermute_b32 v183, v149, v181
	ds_bpermute_b32 v182, v149, v180
	v_mov_b32_e32 v184, v213
	v_mov_b32_e32 v185, v214
	v_mov_b32_e32 v213, v215
	v_pk_add_f32 v[184:185], v[184:185], v[212:213]
	s_waitcnt lgkmcnt(0)
	v_pk_add_f32 v[180:181], v[180:181], v[182:183]
	v_mov_b32_e32 v182, v209
	v_mov_b32_e32 v183, v210
	v_mov_b32_e32 v209, v211
	v_pk_add_f32 v[182:183], v[182:183], v[208:209]
	v_mov_b32_e32 v186, v184
	v_mov_b32_e32 v187, v182
	v_mov_b32_e32 v182, v185
	v_rsq_f32_e32 v154, v154
	v_pk_add_f32 v[182:183], v[186:187], v[182:183]
	ds_bpermute_b32 v185, v147, v183
	ds_bpermute_b32 v184, v147, v182
	v_mul_f32_e32 v158, 0x45800000, v153
	v_cndmask_b32_e64 v176, v153, v158, s[0:1]
	v_mul_f32_e32 v153, 0x45800000, v154
	v_pk_fma_f32 v[180:181], v[180:181], s[8:9], v[190:191] op_sel_hi:[1,0,0]
	v_cndmask_b32_e64 v174, v154, v153, s[4:5]
	v_mul_f32_e32 v154, 0x4b800000, v181
	v_cmp_gt_f32_e64 s[0:1], s58, v181
	v_mul_f32_e32 v147, 0x4b800000, v180
	v_cmp_gt_f32_e64 s[4:5], s58, v180
	v_cndmask_b32_e64 v154, v181, v154, s[0:1]
	v_rsq_f32_e32 v151, v151
	v_cndmask_b32_e64 v147, v180, v147, s[4:5]
	s_waitcnt lgkmcnt(0)
	v_pk_add_f32 v[180:181], v[182:183], v[184:185]
	ds_bpermute_b32 v183, v149, v181
	ds_bpermute_b32 v182, v149, v180
	v_rsq_f32_e32 v154, v154
	v_mul_f32_e32 v153, 0x45800000, v151
	v_cndmask_b32_e32 v170, v151, v153, vcc
	v_rsq_f32_e32 v147, v147
	s_waitcnt lgkmcnt(0)
	v_pk_add_f32 v[180:181], v[180:181], v[182:183]
	v_mul_f32_e32 v149, 0x45800000, v154
	v_pk_fma_f32 v[180:181], v[180:181], s[8:9], v[190:191] op_sel_hi:[1,0,0]
	v_cndmask_b32_e64 v166, v154, v149, s[0:1]
	v_mul_f32_e32 v151, 0x4b800000, v181
	v_cmp_gt_f32_e32 vcc, s58, v181
	v_mul_f32_e32 v153, 0x4b800000, v180
	v_cmp_gt_f32_e64 s[0:1], s58, v180
	v_cndmask_b32_e32 v151, v181, v151, vcc
	v_rsq_f32_e32 v151, v151
	v_cndmask_b32_e64 v153, v180, v153, s[0:1]
	v_rsq_f32_e32 v153, v153
	v_mul_f32_e32 v149, 0x45800000, v147
	v_cndmask_b32_e64 v162, v147, v149, s[4:5]
	v_mul_f32_e32 v147, 0x45800000, v151
	v_cndmask_b32_e32 v158, v151, v147, vcc
	v_mul_f32_e32 v147, 0x45800000, v153
	v_cndmask_b32_e64 v154, v153, v147, s[0:1]
	v_mov_b32_e32 v240, v178
	v_mov_b32_e32 v241, v154
	s_mov_b32 s4, s96
	s_mov_b32 s5, s97
	s_barrier

.LBB0_1093:
	ds_read_b128 v[146:149], v167
	ds_read_b128 v[150:153], v167 offset:1024
	ds_read_b128 v[178:181], v167 offset:2048
	ds_read_b128 v[182:185], v167 offset:3072
	s_add_u32 s28, s0, 0xfffc0080
	s_addc_u32 s29, s1, -1
	s_cmp_eq_u32 s64, 12
	s_cselect_b32 s45, s37, s29
	s_cselect_b32 s44, s60, s28
	s_cselect_b32 s43, s13, s63
	s_cselect_b32 s42, s61, s62
	v_lshl_add_u64 v[156:157], s[0:1], 0, v[138:139]
	s_add_i32 m0, s47, 0xc000
	ds_read_b128 v[186:189], v171
	ds_read_b128 v[196:199], v171 offset:1024
	ds_read_b128 v[200:203], v171 offset:2048
	ds_read_b128 v[204:207], v171 offset:3072
	ds_read_b128 v[208:211], v171 offset:4096
	ds_read_b128 v[212:215], v171 offset:5120
	ds_read_b128 v[216:219], v171 offset:6144
	ds_read_b128 v[220:223], v171 offset:7168
	global_load_lds_dwordx4 v[156:157], off
	v_lshl_add_u64 v[156:157], s[0:1], 0, v[140:141]
	s_add_i32 m0, s47, 0xe000
	s_nop 0
	global_load_lds_dwordx4 v[156:157], off
	s_waitcnt lgkmcnt(8)
	s_barrier
	s_waitcnt lgkmcnt(0)
	s_setprio 1
	s_waitcnt lgkmcnt(0)
	v_mfma_f32_16x16x32_bf16 v[124:127], v[146:149], v[186:189], v[124:127]
	v_mfma_f32_16x16x32_bf16 v[120:123], v[178:181], v[186:189], v[120:123]
	v_mfma_f32_16x16x32_bf16 v[108:111], v[146:149], v[200:203], v[108:111]
	v_mfma_f32_16x16x32_bf16 v[104:107], v[178:181], v[200:203], v[104:107]
	v_mfma_f32_16x16x32_bf16 v[92:95], v[146:149], v[208:211], v[92:95]
	v_mfma_f32_16x16x32_bf16 v[88:91], v[178:181], v[208:211], v[88:91]
	v_mfma_f32_16x16x32_bf16 v[76:79], v[146:149], v[216:219], v[76:79]
	v_mfma_f32_16x16x32_bf16 v[72:75], v[178:181], v[216:219], v[72:75]
	v_mfma_f32_16x16x32_bf16 v[124:127], v[150:153], v[196:199], v[124:127]
	v_mfma_f32_16x16x32_bf16 v[120:123], v[182:185], v[196:199], v[120:123]
	v_mfma_f32_16x16x32_bf16 v[108:111], v[150:153], v[204:207], v[108:111]
	v_mfma_f32_16x16x32_bf16 v[104:107], v[182:185], v[204:207], v[104:107]
	v_mfma_f32_16x16x32_bf16 v[92:95], v[150:153], v[212:215], v[92:95]
	v_mfma_f32_16x16x32_bf16 v[88:91], v[182:185], v[212:215], v[88:91]
	v_mfma_f32_16x16x32_bf16 v[76:79], v[150:153], v[220:223], v[76:79]
	v_mfma_f32_16x16x32_bf16 v[72:75], v[182:185], v[220:223], v[72:75]
	s_setprio 0
	s_barrier
	s_add_i32 s28, s56, s11
	v_lshl_add_u64 v[156:157], s[42:43], 0, v[132:133]
	s_mov_b32 m0, s28
	ds_read_b128 v[224:227], v175
	ds_read_b128 v[228:231], v175 offset:1024
	ds_read_b128 v[232:235], v175 offset:2048
	ds_read_b128 v[236:239], v175 offset:3072
	global_load_lds_dwordx4 v[156:157], off
	v_lshl_add_u64 v[160:161], s[42:43], 0, v[128:129]
	s_add_i32 m0, s28, 0x2000
	s_nop 0
	global_load_lds_dwordx4 v[160:161], off
	s_barrier
	s_waitcnt lgkmcnt(0)
	s_setprio 1
	s_waitcnt lgkmcnt(0)
	v_mfma_f32_16x16x32_bf16 v[116:119], v[224:227], v[186:189], v[116:119]
	v_mfma_f32_16x16x32_bf16 v[112:115], v[232:235], v[186:189], v[112:115]
	v_mfma_f32_16x16x32_bf16 v[100:103], v[224:227], v[200:203], v[100:103]
	v_mfma_f32_16x16x32_bf16 v[96:99], v[232:235], v[200:203], v[96:99]
	v_mfma_f32_16x16x32_bf16 v[84:87], v[224:227], v[208:211], v[84:87]
	v_mfma_f32_16x16x32_bf16 v[80:83], v[232:235], v[208:211], v[80:83]
	v_mfma_f32_16x16x32_bf16 v[68:71], v[224:227], v[216:219], v[68:71]
	v_mfma_f32_16x16x32_bf16 v[64:67], v[232:235], v[216:219], v[64:67]
	v_mfma_f32_16x16x32_bf16 v[116:119], v[228:231], v[196:199], v[116:119]
	v_mfma_f32_16x16x32_bf16 v[112:115], v[236:239], v[196:199], v[112:115]
	v_mfma_f32_16x16x32_bf16 v[100:103], v[228:231], v[204:207], v[100:103]
	v_mfma_f32_16x16x32_bf16 v[96:99], v[236:239], v[204:207], v[96:99]
	v_mfma_f32_16x16x32_bf16 v[84:87], v[228:231], v[212:215], v[84:87]
	v_mfma_f32_16x16x32_bf16 v[80:83], v[236:239], v[212:215], v[80:83]
	v_mfma_f32_16x16x32_bf16 v[68:71], v[228:231], v[220:223], v[68:71]
	v_mfma_f32_16x16x32_bf16 v[64:67], v[236:239], v[220:223], v[64:67]
	s_setprio 0
	s_mov_b32 m0, s47
	v_lshl_add_u64 v[164:165], s[44:45], 0, v[134:135]
	s_barrier
	ds_read_b128 v[186:189], v171 offset:16384
	ds_read_b128 v[196:199], v171 offset:17408
	ds_read_b128 v[200:203], v171 offset:18432
	ds_read_b128 v[204:207], v171 offset:19456
	ds_read_b128 v[208:211], v171 offset:20480
	ds_read_b128 v[212:215], v171 offset:21504
	ds_read_b128 v[216:219], v171 offset:22528
	ds_read_b128 v[220:223], v171 offset:23552
	global_load_lds_dwordx4 v[164:165], off
	v_lshl_add_u64 v[168:169], s[44:45], 0, v[130:131]
	s_mov_b32 m0, s48
	s_nop 0
	global_load_lds_dwordx4 v[168:169], off
	s_barrier
	s_waitcnt lgkmcnt(0)
	s_setprio 1
	s_waitcnt lgkmcnt(0)
	v_mfma_f32_16x16x32_bf16 v[60:63], v[146:149], v[186:189], v[60:63]
	v_mfma_f32_16x16x32_bf16 v[56:59], v[178:181], v[186:189], v[56:59]
	v_mfma_f32_16x16x32_bf16 v[44:47], v[146:149], v[200:203], v[44:47]
	v_mfma_f32_16x16x32_bf16 v[40:43], v[178:181], v[200:203], v[40:43]
	v_mfma_f32_16x16x32_bf16 v[28:31], v[146:149], v[208:211], v[28:31]
	v_mfma_f32_16x16x32_bf16 v[24:27], v[178:181], v[208:211], v[24:27]
	v_mfma_f32_16x16x32_bf16 v[12:15], v[146:149], v[216:219], v[12:15]
	v_mfma_f32_16x16x32_bf16 v[8:11], v[178:181], v[216:219], v[8:11]
	v_mfma_f32_16x16x32_bf16 v[60:63], v[150:153], v[196:199], v[60:63]
	v_mfma_f32_16x16x32_bf16 v[56:59], v[182:185], v[196:199], v[56:59]
	v_mfma_f32_16x16x32_bf16 v[44:47], v[150:153], v[204:207], v[44:47]
	v_mfma_f32_16x16x32_bf16 v[40:43], v[182:185], v[204:207], v[40:43]
	v_mfma_f32_16x16x32_bf16 v[28:31], v[150:153], v[212:215], v[28:31]
	v_mfma_f32_16x16x32_bf16 v[24:27], v[182:185], v[212:215], v[24:27]
	v_mfma_f32_16x16x32_bf16 v[12:15], v[150:153], v[220:223], v[12:15]
	v_mfma_f32_16x16x32_bf16 v[8:11], v[182:185], v[220:223], v[8:11]
	s_setprio 0
	s_barrier
	s_add_u32 s66, s42, 0x40000
	s_addc_u32 s67, s43, 0
	s_add_i32 s28, s57, s11
	v_lshl_add_u64 v[146:147], s[66:67], 0, v[132:133]
	s_mov_b32 m0, s28
	s_nop 0
	global_load_lds_dwordx4 v[146:147], off
	v_lshl_add_u64 v[146:147], s[66:67], 0, v[128:129]
	s_add_i32 m0, s28, 0x2000
	s_nop 0
	global_load_lds_dwordx4 v[146:147], off
	s_waitcnt vmcnt(6)
	s_barrier
	s_setprio 1
	v_mfma_f32_16x16x32_bf16 v[52:55], v[224:227], v[186:189], v[52:55]
	v_mfma_f32_16x16x32_bf16 v[48:51], v[232:235], v[186:189], v[48:51]
	v_mfma_f32_16x16x32_bf16 v[36:39], v[224:227], v[200:203], v[36:39]
	v_mfma_f32_16x16x32_bf16 v[32:35], v[232:235], v[200:203], v[32:35]
	v_mfma_f32_16x16x32_bf16 v[20:23], v[224:227], v[208:211], v[20:23]
	v_mfma_f32_16x16x32_bf16 v[16:19], v[232:235], v[208:211], v[16:19]
	v_mfma_f32_16x16x32_bf16 v[4:7], v[224:227], v[216:219], v[4:7]
	v_mfma_f32_16x16x32_bf16 v[0:3], v[232:235], v[216:219], v[0:3]
	v_mfma_f32_16x16x32_bf16 v[52:55], v[228:231], v[196:199], v[52:55]
	v_mfma_f32_16x16x32_bf16 v[48:51], v[236:239], v[196:199], v[48:51]
	v_mfma_f32_16x16x32_bf16 v[36:39], v[228:231], v[204:207], v[36:39]
	v_mfma_f32_16x16x32_bf16 v[32:35], v[236:239], v[204:207], v[32:35]
	v_mfma_f32_16x16x32_bf16 v[20:23], v[228:231], v[212:215], v[20:23]
	v_mfma_f32_16x16x32_bf16 v[16:19], v[236:239], v[212:215], v[16:19]
	v_mfma_f32_16x16x32_bf16 v[4:7], v[228:231], v[220:223], v[4:7]
	v_mfma_f32_16x16x32_bf16 v[0:3], v[236:239], v[220:223], v[0:3]
	s_setprio 0
	s_add_i32 s28, 0, 0x18000
	v_add_u32_e32 v154, s28, v159
	s_barrier
	ds_read_b128 v[146:149], v154
	ds_read_b128 v[150:153], v154 offset:1024
	ds_read_b128 v[178:181], v154 offset:2048
	ds_read_b128 v[182:185], v154 offset:3072
	s_add_u32 s44, s44, 0x40000
	s_addc_u32 s45, s45, 0
	s_mov_b32 m0, s49
	v_lshl_add_u64 v[172:173], s[44:45], 0, v[134:135]
	ds_read_b128 v[186:189], v171 offset:32768
	ds_read_b128 v[196:199], v171 offset:33792
	ds_read_b128 v[200:203], v171 offset:34816
	ds_read_b128 v[204:207], v171 offset:35840
	ds_read_b128 v[208:211], v171 offset:36864
	ds_read_b128 v[212:215], v171 offset:37888
	ds_read_b128 v[216:219], v171 offset:38912
	ds_read_b128 v[220:223], v171 offset:39936
	global_load_lds_dwordx4 v[172:173], off
	v_lshl_add_u64 v[172:173], s[44:45], 0, v[130:131]
	s_mov_b32 m0, s50
	s_nop 0
	global_load_lds_dwordx4 v[172:173], off
	s_waitcnt lgkmcnt(8)
	s_barrier
	s_waitcnt lgkmcnt(0)
	s_setprio 1
	s_waitcnt lgkmcnt(0)
	v_mfma_f32_16x16x32_bf16 v[124:127], v[146:149], v[186:189], v[124:127]
	v_mfma_f32_16x16x32_bf16 v[120:123], v[178:181], v[186:189], v[120:123]
	v_mfma_f32_16x16x32_bf16 v[108:111], v[146:149], v[200:203], v[108:111]
	v_mfma_f32_16x16x32_bf16 v[104:107], v[178:181], v[200:203], v[104:107]
	v_mfma_f32_16x16x32_bf16 v[92:95], v[146:149], v[208:211], v[92:95]
	v_mfma_f32_16x16x32_bf16 v[88:91], v[178:181], v[208:211], v[88:91]
	v_mfma_f32_16x16x32_bf16 v[76:79], v[146:149], v[216:219], v[76:79]
	v_mfma_f32_16x16x32_bf16 v[72:75], v[178:181], v[216:219], v[72:75]
	v_mfma_f32_16x16x32_bf16 v[124:127], v[150:153], v[196:199], v[124:127]
	v_mfma_f32_16x16x32_bf16 v[120:123], v[182:185], v[196:199], v[120:123]
	v_mfma_f32_16x16x32_bf16 v[108:111], v[150:153], v[204:207], v[108:111]
	v_mfma_f32_16x16x32_bf16 v[104:107], v[182:185], v[204:207], v[104:107]
	v_mfma_f32_16x16x32_bf16 v[92:95], v[150:153], v[212:215], v[92:95]
	v_mfma_f32_16x16x32_bf16 v[88:91], v[182:185], v[212:215], v[88:91]
	v_mfma_f32_16x16x32_bf16 v[76:79], v[150:153], v[220:223], v[76:79]
	v_mfma_f32_16x16x32_bf16 v[72:75], v[182:185], v[220:223], v[72:75]
	s_setprio 0
	s_barrier
	s_add_i32 s29, 0, 0x1c000
	s_add_i32 s28, s28, s11
	v_add_u32_e32 v154, s29, v159
	v_lshl_add_u64 v[156:157], v[156:157], 0, s[6:7]
	s_mov_b32 m0, s28
	ds_read_b128 v[224:227], v154
	ds_read_b128 v[228:231], v154 offset:1024
	ds_read_b128 v[232:235], v154 offset:2048
	ds_read_b128 v[236:239], v154 offset:3072
	global_load_lds_dwordx4 v[156:157], off
	v_lshl_add_u64 v[156:157], v[160:161], 0, s[6:7]
	s_add_i32 m0, s28, 0x2000
	s_nop 0
	global_load_lds_dwordx4 v[156:157], off
	s_barrier
	s_waitcnt lgkmcnt(0)
	s_setprio 1
	s_waitcnt lgkmcnt(0)
	v_mfma_f32_16x16x32_bf16 v[116:119], v[224:227], v[186:189], v[116:119]
	v_mfma_f32_16x16x32_bf16 v[112:115], v[232:235], v[186:189], v[112:115]
	v_mfma_f32_16x16x32_bf16 v[100:103], v[224:227], v[200:203], v[100:103]
	v_mfma_f32_16x16x32_bf16 v[96:99], v[232:235], v[200:203], v[96:99]
	v_mfma_f32_16x16x32_bf16 v[84:87], v[224:227], v[208:211], v[84:87]
	v_mfma_f32_16x16x32_bf16 v[80:83], v[232:235], v[208:211], v[80:83]
	v_mfma_f32_16x16x32_bf16 v[68:71], v[224:227], v[216:219], v[68:71]
	v_mfma_f32_16x16x32_bf16 v[64:67], v[232:235], v[216:219], v[64:67]
	v_mfma_f32_16x16x32_bf16 v[116:119], v[228:231], v[196:199], v[116:119]
	v_mfma_f32_16x16x32_bf16 v[112:115], v[236:239], v[196:199], v[112:115]
	v_mfma_f32_16x16x32_bf16 v[100:103], v[228:231], v[204:207], v[100:103]
	v_mfma_f32_16x16x32_bf16 v[96:99], v[236:239], v[204:207], v[96:99]
	v_mfma_f32_16x16x32_bf16 v[84:87], v[228:231], v[212:215], v[84:87]
	v_mfma_f32_16x16x32_bf16 v[80:83], v[236:239], v[212:215], v[80:83]
	v_mfma_f32_16x16x32_bf16 v[68:71], v[228:231], v[220:223], v[68:71]
	v_mfma_f32_16x16x32_bf16 v[64:67], v[236:239], v[220:223], v[64:67]
	s_setprio 0
	s_mov_b32 m0, s53
	v_lshl_add_u64 v[156:157], v[164:165], 0, s[6:7]
	s_barrier
	ds_read_b128 v[186:189], v171 offset:49152
	ds_read_b128 v[196:199], v171 offset:50176
	ds_read_b128 v[200:203], v171 offset:51200
	ds_read_b128 v[204:207], v171 offset:52224
	ds_read_b128 v[208:211], v171 offset:53248
	ds_read_b128 v[212:215], v171 offset:54272
	ds_read_b128 v[216:219], v171 offset:55296
	ds_read_b128 v[220:223], v171 offset:56320
	global_load_lds_dwordx4 v[156:157], off
	v_lshl_add_u64 v[156:157], v[168:169], 0, s[6:7]
	s_mov_b32 m0, s54
	s_nop 0
	global_load_lds_dwordx4 v[156:157], off
	s_barrier
	s_waitcnt lgkmcnt(0)
	s_setprio 1
	s_waitcnt lgkmcnt(0)
	v_mfma_f32_16x16x32_bf16 v[60:63], v[146:149], v[186:189], v[60:63]
	v_mfma_f32_16x16x32_bf16 v[56:59], v[178:181], v[186:189], v[56:59]
	v_mfma_f32_16x16x32_bf16 v[44:47], v[146:149], v[200:203], v[44:47]
	v_mfma_f32_16x16x32_bf16 v[40:43], v[178:181], v[200:203], v[40:43]
	v_mfma_f32_16x16x32_bf16 v[28:31], v[146:149], v[208:211], v[28:31]
	v_mfma_f32_16x16x32_bf16 v[24:27], v[178:181], v[208:211], v[24:27]
	v_mfma_f32_16x16x32_bf16 v[12:15], v[146:149], v[216:219], v[12:15]
	v_mfma_f32_16x16x32_bf16 v[8:11], v[178:181], v[216:219], v[8:11]
	v_mfma_f32_16x16x32_bf16 v[60:63], v[150:153], v[196:199], v[60:63]
	v_mfma_f32_16x16x32_bf16 v[56:59], v[182:185], v[196:199], v[56:59]
	v_mfma_f32_16x16x32_bf16 v[44:47], v[150:153], v[204:207], v[44:47]
	v_mfma_f32_16x16x32_bf16 v[40:43], v[182:185], v[204:207], v[40:43]
	v_mfma_f32_16x16x32_bf16 v[28:31], v[150:153], v[212:215], v[28:31]
	v_mfma_f32_16x16x32_bf16 v[24:27], v[182:185], v[212:215], v[24:27]
	v_mfma_f32_16x16x32_bf16 v[12:15], v[150:153], v[220:223], v[12:15]
	v_mfma_f32_16x16x32_bf16 v[8:11], v[182:185], v[220:223], v[8:11]
	s_setprio 0
	s_barrier
	s_add_u32 s42, s42, 0x40080
	s_addc_u32 s43, s43, 0
	s_add_i32 s28, s29, s11
	v_lshl_add_u64 v[146:147], s[42:43], 0, v[132:133]
	s_mov_b32 m0, s28
	s_nop 0
	global_load_lds_dwordx4 v[146:147], off
	v_lshl_add_u64 v[146:147], s[42:43], 0, v[128:129]
	s_add_i32 m0, s28, 0x2000
	s_nop 0
	global_load_lds_dwordx4 v[146:147], off
	s_waitcnt vmcnt(6)
	s_barrier
	s_setprio 1
	v_mfma_f32_16x16x32_bf16 v[52:55], v[224:227], v[186:189], v[52:55]
	v_mfma_f32_16x16x32_bf16 v[48:51], v[232:235], v[186:189], v[48:51]
	v_mfma_f32_16x16x32_bf16 v[36:39], v[224:227], v[200:203], v[36:39]
	v_mfma_f32_16x16x32_bf16 v[32:35], v[232:235], v[200:203], v[32:35]
	v_mfma_f32_16x16x32_bf16 v[20:23], v[224:227], v[208:211], v[20:23]
	v_mfma_f32_16x16x32_bf16 v[16:19], v[232:235], v[208:211], v[16:19]
	v_mfma_f32_16x16x32_bf16 v[4:7], v[224:227], v[216:219], v[4:7]
	v_mfma_f32_16x16x32_bf16 v[0:3], v[232:235], v[216:219], v[0:3]
	v_mfma_f32_16x16x32_bf16 v[52:55], v[228:231], v[196:199], v[52:55]
	v_mfma_f32_16x16x32_bf16 v[48:51], v[236:239], v[196:199], v[48:51]
	v_mfma_f32_16x16x32_bf16 v[36:39], v[228:231], v[204:207], v[36:39]
	v_mfma_f32_16x16x32_bf16 v[32:35], v[236:239], v[204:207], v[32:35]
	v_mfma_f32_16x16x32_bf16 v[20:23], v[228:231], v[212:215], v[20:23]
	v_mfma_f32_16x16x32_bf16 v[16:19], v[236:239], v[212:215], v[16:19]
	v_mfma_f32_16x16x32_bf16 v[4:7], v[228:231], v[220:223], v[4:7]
	v_mfma_f32_16x16x32_bf16 v[0:3], v[236:239], v[220:223], v[0:3]
	s_setprio 0
	s_add_i32 s64, s64, 2
	s_add_u32 s0, s0, 0x100
	s_addc_u32 s1, s1, 0
	s_add_u32 s62, s62, 0x100
	s_addc_u32 s63, s63, 0
	s_cmp_gt_u32 s64, 13
	s_barrier
	s_cbranch_scc0 .LBB0_1093
	v_lshl_add_u32 v168, s4, 8, v155
	v_or_b32_e32 v164, 16, v168
	v_or_b32_e32 v160, 32, v168
	v_or_b32_e32 v156, 48, v168
	v_add_u32_e32 v152, 0x80, v168
	v_add_u32_e32 v150, 0x90, v168
	v_add_u32_e32 v148, 0xa0, v168
	v_add_u32_e32 v146, 0xb0, v168
	v_lshl_or_b32 v172, s5, 7, v163
	v_mov_b32_e32 v178, v240
	v_mov_b32_e32 v179, v240
	v_mov_b32_e32 v154, v241
	s_and_b32 s0, s36, 0x7f
	v_lshl_add_u32 v228, s0, 8, v155
	v_mov_b32_e32 v229, 0
	v_lshlrev_b32_e32 v228, 6, v228
	v_lshl_add_u64 v[230:231], v[136:137], 0, v[228:229]
	v_mov_b32_e32 v228, 0x2000
	v_lshl_add_u64 v[232:233], v[230:231], 0, v[228:229]
	global_load_dwordx4 v[216:219], v[230:231], off
	global_load_dwordx4 v[220:223], v[230:231], off offset:1024
	global_load_dwordx4 v[224:227], v[230:231], off offset:2048
	global_load_dwordx4 v[196:199], v[230:231], off offset:3072
	global_load_dwordx4 v[200:203], v[232:233], off
	global_load_dwordx4 v[204:207], v[232:233], off offset:1024
	global_load_dwordx4 v[208:211], v[232:233], off offset:2048
	global_load_dwordx4 v[212:215], v[232:233], off offset:3072
	v_pk_mul_f32 v[124:125], v[124:125], v[178:179] op_sel_hi:[1,0]
	v_pk_mul_f32 v[126:127], v[126:127], v[178:179] op_sel_hi:[1,0]
	v_mul_f32_e32 v147, 0xbfb8aa3b, v124
	v_exp_f32_e32 v147, v147
	v_mul_f32_e32 v149, 0xbfb8aa3b, v125
	v_exp_f32_e32 v149, v149
	v_mul_f32_e32 v151, 0xbfb8aa3b, v127
	v_add_f32_e32 v147, 1.0, v147
	v_rcp_f32_e32 v180, v147
	v_add_f32_e32 v147, 1.0, v149
	v_mul_f32_e32 v149, 0xbfb8aa3b, v126
	v_exp_f32_e32 v149, v149
	v_exp_f32_e32 v151, v151
	v_rcp_f32_e32 v181, v147
	v_pk_mul_f32 v[116:117], v[116:117], v[178:179] op_sel_hi:[1,0]
	v_add_f32_e32 v147, 1.0, v149
	v_rcp_f32_e32 v182, v147
	v_add_f32_e32 v147, 1.0, v151
	v_rcp_f32_e32 v183, v147
	v_pk_mul_f32 v[124:125], v[124:125], v[180:181]
	v_pk_mul_f32 v[120:121], v[120:121], v[178:179] op_sel_hi:[1,0]
	v_pk_mul_f32 v[116:117], v[116:117], v[124:125]
	v_pk_mul_f32 v[124:125], v[126:127], v[182:183]
	v_mul_f32_e32 v126, 0xbfb8aa3b, v120
	v_exp_f32_e32 v126, v126
	v_pk_mul_f32 v[118:119], v[118:119], v[178:179] op_sel_hi:[1,0]
	v_pk_mul_f32 v[122:123], v[122:123], v[178:179] op_sel_hi:[1,0]
	v_pk_mul_f32 v[118:119], v[118:119], v[124:125]
	v_mul_f32_e32 v124, 0xbfb8aa3b, v121
	v_exp_f32_e32 v125, v124
	v_add_f32_e32 v124, 1.0, v126
	v_mul_f32_e32 v126, 0xbfb8aa3b, v122
	v_mul_f32_e32 v127, 0xbfb8aa3b, v123
	v_exp_f32_e32 v126, v126
	v_exp_f32_e32 v127, v127
	v_add_f32_e32 v125, 1.0, v125
	v_rcp_f32_e32 v124, v124
	v_rcp_f32_e32 v125, v125
	v_add_f32_e32 v126, 1.0, v126
	v_add_f32_e32 v127, 1.0, v127
	v_rcp_f32_e32 v126, v126
	v_rcp_f32_e32 v127, v127
	v_pk_mul_f32 v[112:113], v[112:113], v[178:179] op_sel_hi:[1,0]
	v_pk_mul_f32 v[120:121], v[120:121], v[124:125]
	v_pk_mul_f32 v[114:115], v[114:115], v[178:179] op_sel_hi:[1,0]
	v_pk_mul_f32 v[112:113], v[112:113], v[120:121]
	v_pk_mul_f32 v[120:121], v[122:123], v[126:127]
	v_ashrrev_i32_e32 v173, 31, v172
	v_pk_mul_f32 v[114:115], v[114:115], v[120:121]
	v_cvt_pk_bf16_f32 v116, v116, v117
	v_cvt_pk_bf16_f32 v117, v118, v119
	v_cvt_pk_bf16_f32 v118, v112, v113
	v_mov_b64_e32 v[112:113], s[20:21]
	v_cvt_pk_bf16_f32 v119, v114, v115
	v_mad_i64_i32 v[120:121], s[0:1], v168, s59, v[112:113]
	v_lshlrev_b64 v[114:115], 1, v[172:173]
	v_lshl_add_u64 v[120:121], v[120:121], 0, v[114:115]
	v_pk_mul_f32 v[108:109], v[108:109], v[176:177] op_sel_hi:[1,0]
	global_store_dwordx4 v[120:121], v[116:119], off
	v_mul_f32_e32 v122, 0xbfb8aa3b, v108
	v_pk_mul_f32 v[110:111], v[110:111], v[176:177] op_sel_hi:[1,0]
	v_mul_f32_e32 v116, 0xbfb8aa3b, v109
	v_exp_f32_e32 v122, v122
	v_exp_f32_e32 v117, v116
	v_mul_f32_e32 v118, 0xbfb8aa3b, v110
	v_mul_f32_e32 v119, 0xbfb8aa3b, v111
	v_exp_f32_e32 v118, v118
	v_exp_f32_e32 v119, v119
	v_add_f32_e32 v116, 1.0, v122
	v_add_f32_e32 v117, 1.0, v117
	v_rcp_f32_e32 v116, v116
	v_rcp_f32_e32 v117, v117
	v_add_f32_e32 v118, 1.0, v118
	v_add_f32_e32 v119, 1.0, v119
	v_rcp_f32_e32 v118, v118
	v_rcp_f32_e32 v119, v119
	v_pk_mul_f32 v[100:101], v[100:101], v[176:177] op_sel_hi:[1,0]
	v_pk_mul_f32 v[108:109], v[108:109], v[116:117]
	v_pk_mul_f32 v[104:105], v[104:105], v[176:177] op_sel_hi:[1,0]
	v_pk_mul_f32 v[100:101], v[100:101], v[108:109]
	v_pk_mul_f32 v[108:109], v[110:111], v[118:119]
	v_mul_f32_e32 v110, 0xbfb8aa3b, v104
	v_exp_f32_e32 v110, v110
	v_pk_mul_f32 v[102:103], v[102:103], v[176:177] op_sel_hi:[1,0]
	v_pk_mul_f32 v[106:107], v[106:107], v[176:177] op_sel_hi:[1,0]
	v_pk_mul_f32 v[102:103], v[102:103], v[108:109]
	v_mul_f32_e32 v108, 0xbfb8aa3b, v105
	v_exp_f32_e32 v109, v108
	v_add_f32_e32 v108, 1.0, v110
	v_mul_f32_e32 v110, 0xbfb8aa3b, v106
	v_mul_f32_e32 v111, 0xbfb8aa3b, v107
	v_exp_f32_e32 v110, v110
	v_exp_f32_e32 v111, v111
	v_add_f32_e32 v109, 1.0, v109
	v_rcp_f32_e32 v108, v108
	v_rcp_f32_e32 v109, v109
	v_add_f32_e32 v110, 1.0, v110
	v_add_f32_e32 v111, 1.0, v111
	v_rcp_f32_e32 v110, v110
	v_rcp_f32_e32 v111, v111
	v_pk_mul_f32 v[96:97], v[96:97], v[176:177] op_sel_hi:[1,0]
	v_pk_mul_f32 v[104:105], v[104:105], v[108:109]
	v_pk_mul_f32 v[92:93], v[92:93], v[174:175] op_sel_hi:[1,0]
	v_pk_mul_f32 v[104:105], v[96:97], v[104:105]
	v_pk_mul_f32 v[96:97], v[98:99], v[176:177] op_sel_hi:[1,0]
	v_pk_mul_f32 v[98:99], v[106:107], v[110:111]
	v_pk_mul_f32 v[94:95], v[94:95], v[174:175] op_sel_hi:[1,0]
	v_pk_mul_f32 v[106:107], v[96:97], v[98:99]
	v_cvt_pk_bf16_f32 v96, v100, v101
	v_mad_i64_i32 v[100:101], s[0:1], v164, s59, v[112:113]
	v_cvt_pk_bf16_f32 v97, v102, v103
	v_cvt_pk_bf16_f32 v98, v104, v105
	v_cvt_pk_bf16_f32 v99, v106, v107
	v_lshl_add_u64 v[100:101], v[100:101], 0, v[114:115]
	v_mul_f32_e32 v102, 0xbfb8aa3b, v92
	global_store_dwordx4 v[100:101], v[96:99], off
	v_exp_f32_e32 v102, v102
	v_pk_mul_f32 v[84:85], v[84:85], v[174:175] op_sel_hi:[1,0]
	v_mul_f32_e32 v96, 0xbfb8aa3b, v93
	v_exp_f32_e32 v97, v96
	v_mul_f32_e32 v98, 0xbfb8aa3b, v94
	v_mul_f32_e32 v99, 0xbfb8aa3b, v95
	v_exp_f32_e32 v98, v98
	v_exp_f32_e32 v99, v99
	v_add_f32_e32 v96, 1.0, v102
	v_add_f32_e32 v97, 1.0, v97
	v_rcp_f32_e32 v96, v96
	v_rcp_f32_e32 v97, v97
	v_add_f32_e32 v98, 1.0, v98
	v_add_f32_e32 v99, 1.0, v99
	v_rcp_f32_e32 v98, v98
	v_rcp_f32_e32 v99, v99
	v_pk_mul_f32 v[92:93], v[92:93], v[96:97]
	v_pk_mul_f32 v[88:89], v[88:89], v[174:175] op_sel_hi:[1,0]
	v_pk_mul_f32 v[84:85], v[84:85], v[92:93]
	v_pk_mul_f32 v[92:93], v[94:95], v[98:99]
	v_mul_f32_e32 v94, 0xbfb8aa3b, v88
	v_exp_f32_e32 v94, v94
	v_pk_mul_f32 v[86:87], v[86:87], v[174:175] op_sel_hi:[1,0]
	v_pk_mul_f32 v[90:91], v[90:91], v[174:175] op_sel_hi:[1,0]
	v_pk_mul_f32 v[86:87], v[86:87], v[92:93]
	v_mul_f32_e32 v92, 0xbfb8aa3b, v89
	v_exp_f32_e32 v93, v92
	v_add_f32_e32 v92, 1.0, v94
	v_mul_f32_e32 v94, 0xbfb8aa3b, v90
	v_mul_f32_e32 v95, 0xbfb8aa3b, v91
	v_exp_f32_e32 v94, v94
	v_exp_f32_e32 v95, v95
	v_add_f32_e32 v93, 1.0, v93
	v_rcp_f32_e32 v92, v92
	v_rcp_f32_e32 v93, v93
	v_add_f32_e32 v94, 1.0, v94
	v_add_f32_e32 v95, 1.0, v95
	v_rcp_f32_e32 v94, v94
	v_rcp_f32_e32 v95, v95
	v_pk_mul_f32 v[80:81], v[80:81], v[174:175] op_sel_hi:[1,0]
	v_pk_mul_f32 v[88:89], v[88:89], v[92:93]
	v_pk_mul_f32 v[76:77], v[76:77], v[170:171] op_sel_hi:[1,0]
	v_pk_mul_f32 v[88:89], v[80:81], v[88:89]
	v_pk_mul_f32 v[80:81], v[82:83], v[174:175] op_sel_hi:[1,0]
	v_pk_mul_f32 v[82:83], v[90:91], v[94:95]
	v_pk_mul_f32 v[78:79], v[78:79], v[170:171] op_sel_hi:[1,0]
	v_pk_mul_f32 v[90:91], v[80:81], v[82:83]
	v_cvt_pk_bf16_f32 v80, v84, v85
	v_mad_i64_i32 v[84:85], s[0:1], v160, s59, v[112:113]
	v_cvt_pk_bf16_f32 v81, v86, v87
	v_cvt_pk_bf16_f32 v82, v88, v89
	v_cvt_pk_bf16_f32 v83, v90, v91
	v_lshl_add_u64 v[84:85], v[84:85], 0, v[114:115]
	v_mul_f32_e32 v86, 0xbfb8aa3b, v76
	global_store_dwordx4 v[84:85], v[80:83], off
	v_exp_f32_e32 v86, v86
	v_pk_mul_f32 v[68:69], v[68:69], v[170:171] op_sel_hi:[1,0]
	v_mul_f32_e32 v80, 0xbfb8aa3b, v77
	v_exp_f32_e32 v81, v80
	v_mul_f32_e32 v82, 0xbfb8aa3b, v78
	v_mul_f32_e32 v83, 0xbfb8aa3b, v79
	v_exp_f32_e32 v82, v82
	v_exp_f32_e32 v83, v83
	v_add_f32_e32 v80, 1.0, v86
	v_add_f32_e32 v81, 1.0, v81
	v_rcp_f32_e32 v80, v80
	v_rcp_f32_e32 v81, v81
	v_add_f32_e32 v82, 1.0, v82
	v_add_f32_e32 v83, 1.0, v83
	v_rcp_f32_e32 v82, v82
	v_rcp_f32_e32 v83, v83
	v_pk_mul_f32 v[76:77], v[76:77], v[80:81]
	v_pk_mul_f32 v[72:73], v[72:73], v[170:171] op_sel_hi:[1,0]
	v_pk_mul_f32 v[68:69], v[68:69], v[76:77]
	v_pk_mul_f32 v[76:77], v[78:79], v[82:83]
	v_mul_f32_e32 v78, 0xbfb8aa3b, v72
	v_exp_f32_e32 v78, v78
	v_pk_mul_f32 v[70:71], v[70:71], v[170:171] op_sel_hi:[1,0]
	v_pk_mul_f32 v[74:75], v[74:75], v[170:171] op_sel_hi:[1,0]
	v_pk_mul_f32 v[70:71], v[70:71], v[76:77]
	v_mul_f32_e32 v76, 0xbfb8aa3b, v73
	v_exp_f32_e32 v77, v76
	v_add_f32_e32 v76, 1.0, v78
	v_mul_f32_e32 v78, 0xbfb8aa3b, v74
	v_mul_f32_e32 v79, 0xbfb8aa3b, v75
	v_exp_f32_e32 v78, v78
	v_exp_f32_e32 v79, v79
	v_add_f32_e32 v77, 1.0, v77
	v_rcp_f32_e32 v76, v76
	v_rcp_f32_e32 v77, v77
	v_add_f32_e32 v78, 1.0, v78
	v_add_f32_e32 v79, 1.0, v79
	v_rcp_f32_e32 v78, v78
	v_rcp_f32_e32 v79, v79
	v_pk_mul_f32 v[64:65], v[64:65], v[170:171] op_sel_hi:[1,0]
	v_pk_mul_f32 v[72:73], v[72:73], v[76:77]
	v_pk_mul_f32 v[60:61], v[60:61], v[166:167] op_sel_hi:[1,0]
	v_pk_mul_f32 v[72:73], v[64:65], v[72:73]
	v_pk_mul_f32 v[64:65], v[66:67], v[170:171] op_sel_hi:[1,0]
	v_pk_mul_f32 v[66:67], v[74:75], v[78:79]
	v_pk_mul_f32 v[62:63], v[62:63], v[166:167] op_sel_hi:[1,0]
	v_pk_mul_f32 v[74:75], v[64:65], v[66:67]
	v_cvt_pk_bf16_f32 v64, v68, v69
	v_mad_i64_i32 v[68:69], s[0:1], v156, s59, v[112:113]
	v_cvt_pk_bf16_f32 v65, v70, v71
	v_cvt_pk_bf16_f32 v66, v72, v73
	v_cvt_pk_bf16_f32 v67, v74, v75
	v_lshl_add_u64 v[68:69], v[68:69], 0, v[114:115]
	v_mul_f32_e32 v70, 0xbfb8aa3b, v60
	global_store_dwordx4 v[68:69], v[64:67], off
	v_exp_f32_e32 v70, v70
	v_pk_mul_f32 v[52:53], v[52:53], v[166:167] op_sel_hi:[1,0]
	v_mul_f32_e32 v64, 0xbfb8aa3b, v61
	v_exp_f32_e32 v65, v64
	v_mul_f32_e32 v66, 0xbfb8aa3b, v62
	v_mul_f32_e32 v67, 0xbfb8aa3b, v63
	v_exp_f32_e32 v66, v66
	v_exp_f32_e32 v67, v67
	v_add_f32_e32 v64, 1.0, v70
	v_add_f32_e32 v65, 1.0, v65
	v_rcp_f32_e32 v64, v64
	v_rcp_f32_e32 v65, v65
	v_add_f32_e32 v66, 1.0, v66
	v_add_f32_e32 v67, 1.0, v67
	v_rcp_f32_e32 v66, v66
	v_rcp_f32_e32 v67, v67
	v_pk_mul_f32 v[60:61], v[60:61], v[64:65]
	v_pk_mul_f32 v[56:57], v[56:57], v[166:167] op_sel_hi:[1,0]
	v_pk_mul_f32 v[52:53], v[52:53], v[60:61]
	v_pk_mul_f32 v[60:61], v[62:63], v[66:67]
	v_mul_f32_e32 v62, 0xbfb8aa3b, v56
	v_exp_f32_e32 v62, v62
	v_pk_mul_f32 v[54:55], v[54:55], v[166:167] op_sel_hi:[1,0]
	v_pk_mul_f32 v[58:59], v[58:59], v[166:167] op_sel_hi:[1,0]
	v_pk_mul_f32 v[54:55], v[54:55], v[60:61]
	v_mul_f32_e32 v60, 0xbfb8aa3b, v57
	v_exp_f32_e32 v61, v60
	v_add_f32_e32 v60, 1.0, v62
	v_mul_f32_e32 v62, 0xbfb8aa3b, v58
	v_mul_f32_e32 v63, 0xbfb8aa3b, v59
	v_exp_f32_e32 v62, v62
	v_exp_f32_e32 v63, v63
	v_add_f32_e32 v61, 1.0, v61
	v_rcp_f32_e32 v60, v60
	v_rcp_f32_e32 v61, v61
	v_add_f32_e32 v62, 1.0, v62
	v_add_f32_e32 v63, 1.0, v63
	v_rcp_f32_e32 v62, v62
	v_rcp_f32_e32 v63, v63
	v_pk_mul_f32 v[48:49], v[48:49], v[166:167] op_sel_hi:[1,0]
	v_pk_mul_f32 v[56:57], v[56:57], v[60:61]
	v_pk_mul_f32 v[44:45], v[44:45], v[162:163] op_sel_hi:[1,0]
	v_pk_mul_f32 v[56:57], v[48:49], v[56:57]
	v_pk_mul_f32 v[48:49], v[50:51], v[166:167] op_sel_hi:[1,0]
	v_pk_mul_f32 v[50:51], v[58:59], v[62:63]
	v_pk_mul_f32 v[46:47], v[46:47], v[162:163] op_sel_hi:[1,0]
	v_pk_mul_f32 v[58:59], v[48:49], v[50:51]
	v_cvt_pk_bf16_f32 v48, v52, v53
	v_mad_i64_i32 v[52:53], s[0:1], v152, s59, v[112:113]
	v_cvt_pk_bf16_f32 v49, v54, v55
	v_cvt_pk_bf16_f32 v50, v56, v57
	v_cvt_pk_bf16_f32 v51, v58, v59
	v_lshl_add_u64 v[52:53], v[52:53], 0, v[114:115]
	v_mul_f32_e32 v54, 0xbfb8aa3b, v44
	global_store_dwordx4 v[52:53], v[48:51], off
	v_exp_f32_e32 v54, v54
	v_pk_mul_f32 v[36:37], v[36:37], v[162:163] op_sel_hi:[1,0]
	v_mul_f32_e32 v48, 0xbfb8aa3b, v45
	v_exp_f32_e32 v49, v48
	v_mul_f32_e32 v50, 0xbfb8aa3b, v46
	v_mul_f32_e32 v51, 0xbfb8aa3b, v47
	v_exp_f32_e32 v50, v50
	v_exp_f32_e32 v51, v51
	v_add_f32_e32 v48, 1.0, v54
	v_add_f32_e32 v49, 1.0, v49
	v_rcp_f32_e32 v48, v48
	v_rcp_f32_e32 v49, v49
	v_add_f32_e32 v50, 1.0, v50
	v_add_f32_e32 v51, 1.0, v51
	v_rcp_f32_e32 v50, v50
	v_rcp_f32_e32 v51, v51
	v_pk_mul_f32 v[44:45], v[44:45], v[48:49]
	v_pk_mul_f32 v[40:41], v[40:41], v[162:163] op_sel_hi:[1,0]
	v_pk_mul_f32 v[36:37], v[36:37], v[44:45]
	v_pk_mul_f32 v[44:45], v[46:47], v[50:51]
	v_mul_f32_e32 v46, 0xbfb8aa3b, v40
	v_exp_f32_e32 v46, v46
	v_pk_mul_f32 v[38:39], v[38:39], v[162:163] op_sel_hi:[1,0]
	v_pk_mul_f32 v[42:43], v[42:43], v[162:163] op_sel_hi:[1,0]
	v_pk_mul_f32 v[38:39], v[38:39], v[44:45]
	v_mul_f32_e32 v44, 0xbfb8aa3b, v41
	v_exp_f32_e32 v45, v44
	v_add_f32_e32 v44, 1.0, v46
	v_mul_f32_e32 v46, 0xbfb8aa3b, v42
	v_mul_f32_e32 v47, 0xbfb8aa3b, v43
	v_exp_f32_e32 v46, v46
	v_exp_f32_e32 v47, v47
	v_add_f32_e32 v45, 1.0, v45
	v_rcp_f32_e32 v44, v44
	v_rcp_f32_e32 v45, v45
	v_add_f32_e32 v46, 1.0, v46
	v_add_f32_e32 v47, 1.0, v47
	v_rcp_f32_e32 v46, v46
	v_rcp_f32_e32 v47, v47
	v_pk_mul_f32 v[32:33], v[32:33], v[162:163] op_sel_hi:[1,0]
	v_pk_mul_f32 v[40:41], v[40:41], v[44:45]
	v_pk_mul_f32 v[28:29], v[28:29], v[158:159] op_sel_hi:[1,0]
	v_pk_mul_f32 v[40:41], v[32:33], v[40:41]
	v_pk_mul_f32 v[32:33], v[34:35], v[162:163] op_sel_hi:[1,0]
	v_pk_mul_f32 v[34:35], v[42:43], v[46:47]
	v_pk_mul_f32 v[30:31], v[30:31], v[158:159] op_sel_hi:[1,0]
	v_pk_mul_f32 v[42:43], v[32:33], v[34:35]
	v_cvt_pk_bf16_f32 v32, v36, v37
	v_mad_i64_i32 v[36:37], s[0:1], v150, s59, v[112:113]
	v_cvt_pk_bf16_f32 v33, v38, v39
	v_cvt_pk_bf16_f32 v34, v40, v41
	v_cvt_pk_bf16_f32 v35, v42, v43
	v_lshl_add_u64 v[36:37], v[36:37], 0, v[114:115]
	v_mul_f32_e32 v38, 0xbfb8aa3b, v28
	global_store_dwordx4 v[36:37], v[32:35], off
	v_exp_f32_e32 v38, v38
	v_pk_mul_f32 v[20:21], v[20:21], v[158:159] op_sel_hi:[1,0]
	v_mul_f32_e32 v32, 0xbfb8aa3b, v29
	v_exp_f32_e32 v33, v32
	v_mul_f32_e32 v34, 0xbfb8aa3b, v30
	v_mul_f32_e32 v35, 0xbfb8aa3b, v31
	v_exp_f32_e32 v34, v34
	v_exp_f32_e32 v35, v35
	v_add_f32_e32 v32, 1.0, v38
	v_add_f32_e32 v33, 1.0, v33
	v_rcp_f32_e32 v32, v32
	v_rcp_f32_e32 v33, v33
	v_add_f32_e32 v34, 1.0, v34
	v_add_f32_e32 v35, 1.0, v35
	v_rcp_f32_e32 v34, v34
	v_rcp_f32_e32 v35, v35
	v_pk_mul_f32 v[28:29], v[28:29], v[32:33]
	v_pk_mul_f32 v[24:25], v[24:25], v[158:159] op_sel_hi:[1,0]
	v_pk_mul_f32 v[20:21], v[20:21], v[28:29]
	v_pk_mul_f32 v[28:29], v[30:31], v[34:35]
	v_mul_f32_e32 v30, 0xbfb8aa3b, v24
	v_exp_f32_e32 v30, v30
	v_pk_mul_f32 v[22:23], v[22:23], v[158:159] op_sel_hi:[1,0]
	v_pk_mul_f32 v[26:27], v[26:27], v[158:159] op_sel_hi:[1,0]
	v_pk_mul_f32 v[22:23], v[22:23], v[28:29]
	v_mul_f32_e32 v28, 0xbfb8aa3b, v25
	v_exp_f32_e32 v29, v28
	v_add_f32_e32 v28, 1.0, v30
	v_mul_f32_e32 v30, 0xbfb8aa3b, v26
	v_mul_f32_e32 v31, 0xbfb8aa3b, v27
	v_exp_f32_e32 v30, v30
	v_exp_f32_e32 v31, v31
	v_add_f32_e32 v29, 1.0, v29
	v_rcp_f32_e32 v28, v28
	v_rcp_f32_e32 v29, v29
	v_add_f32_e32 v30, 1.0, v30
	v_add_f32_e32 v31, 1.0, v31
	v_rcp_f32_e32 v30, v30
	v_rcp_f32_e32 v31, v31
	v_pk_mul_f32 v[16:17], v[16:17], v[158:159] op_sel_hi:[1,0]
	v_pk_mul_f32 v[24:25], v[24:25], v[28:29]
	v_pk_mul_f32 v[12:13], v[12:13], v[154:155] op_sel_hi:[1,0]
	v_pk_mul_f32 v[24:25], v[16:17], v[24:25]
	v_pk_mul_f32 v[16:17], v[18:19], v[158:159] op_sel_hi:[1,0]
	v_pk_mul_f32 v[18:19], v[26:27], v[30:31]
	v_pk_mul_f32 v[14:15], v[14:15], v[154:155] op_sel_hi:[1,0]
	v_pk_mul_f32 v[26:27], v[16:17], v[18:19]
	v_cvt_pk_bf16_f32 v16, v20, v21
	v_mad_i64_i32 v[20:21], s[0:1], v148, s59, v[112:113]
	v_cvt_pk_bf16_f32 v17, v22, v23
	v_cvt_pk_bf16_f32 v18, v24, v25
	v_cvt_pk_bf16_f32 v19, v26, v27
	v_lshl_add_u64 v[20:21], v[20:21], 0, v[114:115]
	v_mul_f32_e32 v22, 0xbfb8aa3b, v12
	global_store_dwordx4 v[20:21], v[16:19], off
	v_exp_f32_e32 v22, v22
	v_pk_mul_f32 v[4:5], v[4:5], v[154:155] op_sel_hi:[1,0]
	v_mul_f32_e32 v16, 0xbfb8aa3b, v13
	v_exp_f32_e32 v17, v16
	v_mul_f32_e32 v18, 0xbfb8aa3b, v14
	v_mul_f32_e32 v19, 0xbfb8aa3b, v15
	v_exp_f32_e32 v18, v18
	v_exp_f32_e32 v19, v19
	v_add_f32_e32 v16, 1.0, v22
	v_add_f32_e32 v17, 1.0, v17
	v_rcp_f32_e32 v16, v16
	v_rcp_f32_e32 v17, v17
	v_add_f32_e32 v18, 1.0, v18
	v_add_f32_e32 v19, 1.0, v19
	v_rcp_f32_e32 v18, v18
	v_rcp_f32_e32 v19, v19
	v_pk_mul_f32 v[12:13], v[12:13], v[16:17]
	v_pk_mul_f32 v[8:9], v[8:9], v[154:155] op_sel_hi:[1,0]
	v_pk_mul_f32 v[4:5], v[4:5], v[12:13]
	v_pk_mul_f32 v[12:13], v[14:15], v[18:19]
	v_mul_f32_e32 v14, 0xbfb8aa3b, v8
	v_exp_f32_e32 v14, v14
	v_pk_mul_f32 v[6:7], v[6:7], v[154:155] op_sel_hi:[1,0]
	v_pk_mul_f32 v[10:11], v[10:11], v[154:155] op_sel_hi:[1,0]
	v_pk_mul_f32 v[6:7], v[6:7], v[12:13]
	v_mul_f32_e32 v12, 0xbfb8aa3b, v9
	v_exp_f32_e32 v13, v12
	v_add_f32_e32 v12, 1.0, v14
	v_mul_f32_e32 v14, 0xbfb8aa3b, v10
	v_mul_f32_e32 v15, 0xbfb8aa3b, v11
	v_exp_f32_e32 v14, v14
	v_exp_f32_e32 v15, v15
	v_add_f32_e32 v13, 1.0, v13
	v_rcp_f32_e32 v12, v12
	v_rcp_f32_e32 v13, v13
	v_add_f32_e32 v14, 1.0, v14
	v_add_f32_e32 v15, 1.0, v15
	v_rcp_f32_e32 v14, v14
	v_rcp_f32_e32 v15, v15
	v_pk_mul_f32 v[0:1], v[0:1], v[154:155] op_sel_hi:[1,0]
	v_pk_mul_f32 v[8:9], v[8:9], v[12:13]
	s_and_b64 vcc, exec, s[2:3]
	v_pk_mul_f32 v[8:9], v[0:1], v[8:9]
	v_pk_mul_f32 v[0:1], v[2:3], v[154:155] op_sel_hi:[1,0]
	v_pk_mul_f32 v[2:3], v[10:11], v[14:15]
	s_mov_b32 s5, s12
	v_pk_mul_f32 v[10:11], v[0:1], v[2:3]
	v_cvt_pk_bf16_f32 v0, v4, v5
	v_mad_i64_i32 v[4:5], s[0:1], v146, s59, v[112:113]
	v_cvt_pk_bf16_f32 v1, v6, v7
	v_cvt_pk_bf16_f32 v2, v8, v9
	v_cvt_pk_bf16_f32 v3, v10, v11
	v_lshl_add_u64 v[4:5], v[4:5], 0, v[114:115]
	s_mov_b32 s4, s36
	s_mov_b64 s[42:43], s[40:41]
	s_mov_b64 s[44:45], s[38:39]
	global_store_dwordx4 v[4:5], v[0:3], off
	s_waitcnt vmcnt(8)
	v_mov_b32_e32 v178, v216
	v_mov_b32_e32 v179, v217
	v_mov_b32_e32 v180, v218
	v_mov_b32_e32 v181, v219
	v_mov_b32_e32 v182, v220
	v_mov_b32_e32 v183, v221
	v_mov_b32_e32 v184, v222
	v_mov_b32_e32 v185, v223
	v_mov_b32_e32 v186, v224
	v_mov_b32_e32 v187, v225
	v_mov_b32_e32 v188, v226
	v_mov_b32_e32 v189, v227
	v_and_b32_e32 v147, 64, v177
	v_add_u32_e32 v154, 64, v147
	v_xor_b32_e32 v151, 16, v177
	v_cmp_lt_i32_e32 vcc, v151, v154
	v_xor_b32_e32 v153, 32, v177
	v_mov_b64_e32 v[190:191], s[10:11]
	v_cndmask_b32_e32 v151, v177, v151, vcc
	v_lshlrev_b32_e32 v147, 2, v151
	v_cmp_lt_i32_e32 vcc, v153, v154
	v_mov_b32_e32 v216, v179
	v_mov_b32_e32 v217, v180
	v_mov_b32_e32 v179, v181
	v_mov_b32_e32 v180, v183
	v_mov_b32_e32 v181, v184
	v_mov_b32_e32 v183, v185
	v_pk_add_f32 v[178:179], v[216:217], v[178:179]
	v_pk_add_f32 v[180:181], v[180:181], v[182:183]
	v_mov_b32_e32 v183, v178
	v_mov_b32_e32 v182, v180
	v_mov_b32_e32 v178, v181
	v_mov_b32_e32 v184, v187
	v_mov_b32_e32 v185, v188
	v_mov_b32_e32 v187, v189
	v_mov_b32_e32 v188, v197
	v_mov_b32_e32 v189, v198
	v_mov_b32_e32 v197, v199
	v_pk_add_f32 v[178:179], v[182:183], v[178:179]
	v_pk_add_f32 v[184:185], v[184:185], v[186:187]
	v_pk_add_f32 v[186:187], v[188:189], v[196:197]
	ds_bpermute_b32 v183, v147, v179
	ds_bpermute_b32 v182, v147, v178
	v_mov_b32_e32 v180, v186
	v_mov_b32_e32 v181, v184
	v_mov_b32_e32 v184, v187
	v_pk_add_f32 v[180:181], v[180:181], v[184:185]
	ds_bpermute_b32 v185, v147, v181
	ds_bpermute_b32 v184, v147, v180
	v_cndmask_b32_e32 v153, v177, v153, vcc
	v_lshlrev_b32_e32 v149, 2, v153
	s_waitcnt lgkmcnt(0)
	v_pk_add_f32 v[178:179], v[178:179], v[182:183]
	ds_bpermute_b32 v183, v149, v179
	ds_bpermute_b32 v182, v149, v178
	v_pk_add_f32 v[180:181], v[180:181], v[184:185]
	ds_bpermute_b32 v185, v149, v181
	ds_bpermute_b32 v184, v149, v180
	v_mov_b32_e32 v186, v201
	s_waitcnt lgkmcnt(2)
	v_pk_add_f32 v[178:179], v[178:179], v[182:183]
	v_mov_b32_e32 v187, v202
	v_mov_b32_e32 v201, v203
	v_mov_b32_e32 v188, v205
	v_pk_fma_f32 v[178:179], v[178:179], s[8:9], v[190:191] op_sel_hi:[1,0,0]
	v_mov_b32_e32 v189, v206
	v_mov_b32_e32 v205, v207
	v_pk_add_f32 v[186:187], v[186:187], v[200:201]
	v_mul_f32_e32 v151, 0x4b800000, v179
	v_cmp_gt_f32_e32 vcc, s58, v179
	v_pk_add_f32 v[182:183], v[188:189], v[204:205]
	s_waitcnt lgkmcnt(0)
	v_pk_add_f32 v[180:181], v[180:181], v[184:185]
	v_cndmask_b32_e32 v151, v179, v151, vcc
	v_mov_b32_e32 v184, v182
	v_mov_b32_e32 v185, v186
	v_mov_b32_e32 v186, v183
	v_rsq_f32_e32 v151, v151
	v_pk_add_f32 v[182:183], v[184:185], v[186:187]
	ds_bpermute_b32 v185, v147, v183
	ds_bpermute_b32 v184, v147, v182
	v_pk_fma_f32 v[180:181], v[180:181], s[8:9], v[190:191] op_sel_hi:[1,0,0]
	v_mul_f32_e32 v153, 0x4b800000, v178
	v_cmp_gt_f32_e64 s[0:1], s58, v178
	v_mul_f32_e32 v157, 0x45800000, v151
	v_mul_f32_e32 v154, 0x4b800000, v181
	v_cndmask_b32_e64 v153, v178, v153, s[0:1]
	v_cmp_gt_f32_e64 s[4:5], s58, v181
	v_cndmask_b32_e32 v178, v151, v157, vcc
	v_mul_f32_e32 v151, 0x4b800000, v180
	v_cmp_gt_f32_e32 vcc, s58, v180
	v_cndmask_b32_e64 v154, v181, v154, s[4:5]
	v_rsq_f32_e32 v153, v153
	v_cndmask_b32_e32 v151, v180, v151, vcc
	s_waitcnt lgkmcnt(0)
	v_pk_add_f32 v[180:181], v[182:183], v[184:185]
	ds_bpermute_b32 v183, v149, v181
	ds_bpermute_b32 v182, v149, v180
	v_mov_b32_e32 v184, v213
	v_mov_b32_e32 v185, v214
	v_mov_b32_e32 v213, v215
	v_pk_add_f32 v[184:185], v[184:185], v[212:213]
	s_waitcnt lgkmcnt(0)
	v_pk_add_f32 v[180:181], v[180:181], v[182:183]
	v_mov_b32_e32 v182, v209
	v_mov_b32_e32 v183, v210
	v_mov_b32_e32 v209, v211
	v_pk_add_f32 v[182:183], v[182:183], v[208:209]
	v_mov_b32_e32 v186, v184
	v_mov_b32_e32 v187, v182
	v_mov_b32_e32 v182, v185
	v_rsq_f32_e32 v154, v154
	v_pk_add_f32 v[182:183], v[186:187], v[182:183]
	ds_bpermute_b32 v185, v147, v183
	ds_bpermute_b32 v184, v147, v182
	v_mul_f32_e32 v158, 0x45800000, v153
	v_cndmask_b32_e64 v176, v153, v158, s[0:1]
	v_mul_f32_e32 v153, 0x45800000, v154
	v_pk_fma_f32 v[180:181], v[180:181], s[8:9], v[190:191] op_sel_hi:[1,0,0]
	v_cndmask_b32_e64 v174, v154, v153, s[4:5]
	v_mul_f32_e32 v154, 0x4b800000, v181
	v_cmp_gt_f32_e64 s[0:1], s58, v181
	v_mul_f32_e32 v147, 0x4b800000, v180
	v_cmp_gt_f32_e64 s[4:5], s58, v180
	v_cndmask_b32_e64 v154, v181, v154, s[0:1]
	v_rsq_f32_e32 v151, v151
	v_cndmask_b32_e64 v147, v180, v147, s[4:5]
	s_waitcnt lgkmcnt(0)
	v_pk_add_f32 v[180:181], v[182:183], v[184:185]
	ds_bpermute_b32 v183, v149, v181
	ds_bpermute_b32 v182, v149, v180
	v_rsq_f32_e32 v154, v154
	v_mul_f32_e32 v153, 0x45800000, v151
	v_cndmask_b32_e32 v170, v151, v153, vcc
	v_rsq_f32_e32 v147, v147
	s_waitcnt lgkmcnt(0)
	v_pk_add_f32 v[180:181], v[180:181], v[182:183]
	v_mul_f32_e32 v149, 0x45800000, v154
	v_pk_fma_f32 v[180:181], v[180:181], s[8:9], v[190:191] op_sel_hi:[1,0,0]
	v_cndmask_b32_e64 v166, v154, v149, s[0:1]
	v_mul_f32_e32 v151, 0x4b800000, v181
	v_cmp_gt_f32_e32 vcc, s58, v181
	v_mul_f32_e32 v153, 0x4b800000, v180
	v_cmp_gt_f32_e64 s[0:1], s58, v180
	v_cndmask_b32_e32 v151, v181, v151, vcc
	v_rsq_f32_e32 v151, v151
	v_cndmask_b32_e64 v153, v180, v153, s[0:1]
	v_rsq_f32_e32 v153, v153
	v_mul_f32_e32 v149, 0x45800000, v147
	v_cndmask_b32_e64 v162, v147, v149, s[4:5]
	v_mul_f32_e32 v147, 0x45800000, v151
	v_cndmask_b32_e32 v158, v151, v147, vcc
	v_mul_f32_e32 v147, 0x45800000, v153
	v_cndmask_b32_e64 v154, v153, v147, s[0:1]
	v_mov_b32_e32 v240, v178
	v_mov_b32_e32 v241, v154
	s_and_b64 vcc, exec, s[2:3]
	s_mov_b32 s5, s12
	s_mov_b32 s4, s36
	s_cbranch_vccz .LBB0_1090
	s_waitcnt vmcnt(0)
	s_cmpk_gt_u32 s9, 0xff
	s_cbranch_scc1 .LBB0_1097
	s_barrier
